# static s_setprio 3 for the HGRN chain compute waves (one raise at loop entry, restored at exit); rest as session best
# baseline (speedup 1.0000x reference)
; __device__ __forceinline__ void hgrn_chain(const unsigned char* REC, const float* s0, float* sout, bf16_t* MIX,
;                                            int cidx0, int nchunks, int h, int vhalf, LAS unsigned char* lds, int wave, int lane) {
;     ...
;     for (int c = 0; c < nchunks; ++c) {
;         ch_issue(Ri, lds + islot * CH_SLOT, wave); Ri = Ri < Rlast ? Ri + 8 * REC_STRIDE : Rlast;
;         islot = islot == CH_NS - 1 ? 0 : islot + 1;
;         const LAS unsigned char* R = lds + slot * CH_SLOT;
;         slot = slot == CH_NS - 1 ? 0 : slot + 1;
;         if (comp) {
;             bf16x8 QDf[2][4], KEf[8], ITf, Af[2]; f32x4 DEC[8];
; #pragma unroll
;             for (int kb = 0; kb < 8; ++kb) { DEC[kb] = *(const LAS f32x4*)(R + R_DEC + (16 * kb + 4 * g) * 4); KEf[kb] = *(const LAS bf16x8*)(R + R_KE + ((16 * kb + c16) * 32 + 8 * g) * 2); }
;             ITf = *(const LAS bf16x8*)(R + R_IT + ((v0 + c16) * 32 + 8 * g) * 2);
; #pragma unroll
;             for (int tb = 0; tb < 2; ++tb) {
;                 Af[tb] = *(const LAS bf16x8*)(R + R_A + ((16 * tb + c16) * 32 + 8 * g) * 2);
; #pragma unroll
;                 for (int kk = 0; kk < 4; ++kk) QDf[tb][kk] = *(const LAS bf16x8*)(R + R_QD + ((tb * 4 + kk) * 64 + lane) * 16);
;             }
;             bf16x8 Sb[4];
; #pragma unroll
;             for (int kk = 0; kk < 4; ++kk) {
;                 u32x4 sb; sb.x = cvt_pk_bf16(S[2 * kk][0], S[2 * kk][1]); sb.y = cvt_pk_bf16(S[2 * kk][2], S[2 * kk][3]);
;                 sb.z = cvt_pk_bf16(S[2 * kk + 1][0], S[2 * kk + 1][1]); sb.w = cvt_pk_bf16(S[2 * kk + 1][2], S[2 * kk + 1][3]);
;                 Sb[kk] = __builtin_bit_cast(bf16x8, sb);
;             }
; #pragma unroll
;             for (int kb = 0; kb < 8; ++kb) S[kb] = __builtin_amdgcn_mfma_f32_16x16x32_bf16(KEf[kb], ITf, S[kb] * DEC[kb], 0, 0, 0);
;             f32x4 o0 = {0.f, 0.f, 0.f, 0.f}, o1 = o0;
;             o0 = __builtin_amdgcn_mfma_f32_16x16x32_bf16(ITf, Af[0], o0, 0, 0, 0);
;             o1 = __builtin_amdgcn_mfma_f32_16x16x32_bf16(ITf, Af[1], o1, 0, 0, 0);
; #pragma unroll
;             for (int kk = 0; kk < 4; ++kk) { o0 = __builtin_amdgcn_mfma_f32_16x16x32_bf16(Sb[kk], QDf[0][kk], o0, 0, 0, 0); o1 = __builtin_amdgcn_mfma_f32_16x16x32_bf16(Sb[kk], QDf[1][kk], o1, 0, 0, 0); }
;             u32x2 w; w.x = cvt_pk_bf16(o0[0], o0[1]); w.y = cvt_pk_bf16(o0[2], o0[3]);
.Lch_comp_new:
	v_readlane_b32 s12, v236, 35
	s_mov_b64 s[8:9], -1
	s_cmp_lt_u32 s12, 2
	s_cbranch_scc0 .LBB0_604
	s_setprio 3
.Lch_comp_loop:
	s_mul_i32 s12, s16, 0x6c00
	v_add_u32_e32 v36, s12, v61
	v_add_u32_e32 v39, s12, v120
	v_add_u32_e32 v37, v36, v63
	v_add_u32_e32 v38, v36, v62
	ds_read_b128 v[32:35], v38 offset:16384
	ds_read_b128 v[164:167], v36 offset:26624
	ds_read_b128 v[196:199], v37 offset:8192
	ds_read_b128 v[168:171], v36 offset:26688
	ds_read_b128 v[200:203], v37 offset:9216
	ds_read_b128 v[172:175], v36 offset:26752
	ds_read_b128 v[204:207], v37 offset:10240
	ds_read_b128 v[176:179], v36 offset:26816
	ds_read_b128 v[208:211], v37 offset:11264
	ds_read_b128 v[180:183], v36 offset:26880
	ds_read_b128 v[212:215], v37 offset:12288
	ds_read_b128 v[184:187], v36 offset:26944
	ds_read_b128 v[216:219], v37 offset:13312
	ds_read_b128 v[188:191], v36 offset:27008
	ds_read_b128 v[220:223], v37 offset:14336
	s_mov_b64 s[8:9], 0
	v_cvt_pk_bf16_f32 v110, v28, v29
	v_cvt_pk_bf16_f32 v111, v30, v31
	v_cvt_pk_bf16_f32 v112, v24, v25
	v_cvt_pk_bf16_f32 v113, v26, v27
	v_cvt_pk_bf16_f32 v114, v20, v21
	v_cvt_pk_bf16_f32 v115, v22, v23
	v_cvt_pk_bf16_f32 v116, v16, v17
	v_cvt_pk_bf16_f32 v117, v18, v19
	v_cvt_pk_bf16_f32 v130, v12, v13
	v_cvt_pk_bf16_f32 v131, v14, v15
	v_cvt_pk_bf16_f32 v132, v8, v9
	v_cvt_pk_bf16_f32 v133, v10, v11
	v_cvt_pk_bf16_f32 v134, v4, v5
	v_cvt_pk_bf16_f32 v135, v6, v7
	v_cvt_pk_bf16_f32 v136, v0, v1
	v_cvt_pk_bf16_f32 v137, v2, v3
	s_waitcnt lgkmcnt(12)
	v_pk_mul_f32 v[28:29], v[28:29], v[164:165]
	v_pk_mul_f32 v[30:31], v[30:31], v[166:167]
	ds_read_b128 v[192:195], v36 offset:27072
	ds_read_b128 v[224:227], v37 offset:15360
	v_mfma_f32_16x16x32_bf16 v[28:31], v[196:199], v[32:35], v[28:31]
	s_waitcnt lgkmcnt(12)
	v_pk_mul_f32 v[24:25], v[24:25], v[168:169]
	v_pk_mul_f32 v[26:27], v[26:27], v[170:171]
	ds_read_b128 v[228:231], v37 offset:24576
	ds_read_b128 v[232:235], v37 offset:25600
	v_mfma_f32_16x16x32_bf16 v[24:27], v[200:203], v[32:35], v[24:27]
	s_waitcnt lgkmcnt(12)
	v_pk_mul_f32 v[20:21], v[20:21], v[172:173]
	v_pk_mul_f32 v[22:23], v[22:23], v[174:175]
	ds_read_b128 v[78:81], v39
	ds_read_b128 v[82:85], v39 offset:4096
	v_mfma_f32_16x16x32_bf16 v[20:23], v[204:207], v[32:35], v[20:23]
	s_waitcnt lgkmcnt(12)
	v_pk_mul_f32 v[16:17], v[16:17], v[176:177]
	v_pk_mul_f32 v[18:19], v[18:19], v[178:179]
	ds_read_b128 v[86:89], v39 offset:1024
	ds_read_b128 v[90:93], v39 offset:5120
	v_mfma_f32_16x16x32_bf16 v[16:19], v[208:211], v[32:35], v[16:19]
	s_waitcnt lgkmcnt(12)
	v_pk_mul_f32 v[12:13], v[12:13], v[180:181]
	v_pk_mul_f32 v[14:15], v[14:15], v[182:183]
	ds_read_b128 v[94:97], v39 offset:2048
	ds_read_b128 v[98:101], v39 offset:6144
	v_mfma_f32_16x16x32_bf16 v[12:15], v[212:215], v[32:35], v[12:15]
	s_waitcnt lgkmcnt(12)
	v_pk_mul_f32 v[8:9], v[8:9], v[184:185]
	v_pk_mul_f32 v[10:11], v[10:11], v[186:187]
	ds_read_b128 v[102:105], v39 offset:3072
	ds_read_b128 v[106:109], v39 offset:7168
	v_mfma_f32_16x16x32_bf16 v[8:11], v[216:219], v[32:35], v[8:11]
	s_waitcnt lgkmcnt(12)
	v_pk_mul_f32 v[4:5], v[4:5], v[188:189]
	v_pk_mul_f32 v[6:7], v[6:7], v[190:191]
	s_nop 1
	v_mfma_f32_16x16x32_bf16 v[4:7], v[220:223], v[32:35], v[4:7]
	s_waitcnt lgkmcnt(10)
	v_pk_mul_f32 v[0:1], v[0:1], v[192:193]
	v_pk_mul_f32 v[2:3], v[2:3], v[194:195]
	s_nop 1
	v_mfma_f32_16x16x32_bf16 v[0:3], v[224:227], v[32:35], v[0:3]
	s_waitcnt lgkmcnt(8)
	v_mfma_f32_16x16x32_bf16 v[138:141], v[32:35], v[228:231], 0
	v_mfma_f32_16x16x32_bf16 v[146:149], v[32:35], v[232:235], 0
	s_waitcnt lgkmcnt(7)
	v_mfma_f32_16x16x32_bf16 v[138:141], v[110:113], v[78:81], v[138:141]
	s_waitcnt lgkmcnt(6)
	v_mfma_f32_16x16x32_bf16 v[146:149], v[110:113], v[82:85], v[146:149]
	s_waitcnt lgkmcnt(5)
	v_mfma_f32_16x16x32_bf16 v[138:141], v[114:117], v[86:89], v[138:141]
	s_waitcnt lgkmcnt(4)
	v_mfma_f32_16x16x32_bf16 v[146:149], v[114:117], v[90:93], v[146:149]
	s_waitcnt lgkmcnt(3)
	v_mfma_f32_16x16x32_bf16 v[138:141], v[130:133], v[94:97], v[138:141]
	s_waitcnt lgkmcnt(2)
	v_mfma_f32_16x16x32_bf16 v[146:149], v[130:133], v[98:101], v[146:149]
	s_waitcnt lgkmcnt(1)
	v_mfma_f32_16x16x32_bf16 v[138:141], v[134:137], v[102:105], v[138:141]
	s_waitcnt lgkmcnt(0)
	v_mfma_f32_16x16x32_bf16 v[146:149], v[134:137], v[106:109], v[146:149]
	s_mov_b32 s12, 0xffff0000
	s_nop 6
	v_cvt_pk_bf16_f32 v36, v138, v139
	v_cvt_pk_bf16_f32 v37, v140, v141
	v_add_co_u32_e32 v38, vcc, s12, v48
	v_cvt_pk_bf16_f32 v40, v146, v147
	s_nop 0
	v_addc_co_u32_e32 v39, vcc, -1, v49, vcc
	v_cvt_pk_bf16_f32 v41, v148, v149
	global_store_dwordx2 v[38:39], v[36:37], off
	global_store_dwordx2 v[48:49], v[40:41], off
	s_add_i32 s12, s16, 1
	s_cmp_lg_u32 s16, 3
	s_cselect_b32 s16, s12, 0
	s_add_i32 s11, s11, 1
	s_mov_b64 s[12:13], 0x20000
	v_lshl_add_u64 v[48:49], v[48:49], 0, s[12:13]
	s_waitcnt lgkmcnt(0)
	s_barrier
	s_cmpk_eq_i32 s11, 0x100
	s_cbranch_scc0 .Lch_comp_loop
	s_setprio 0
	s_branch .LBB0_639
